# v71 + grid barrier: first-arriving workgroup of each XCD starts an early non-blocking L2 write-back
# speedup vs baseline: 1.0033x; 1.0033x over previous
.LBB0_62:
	s_or_b64 exec, exec, s[18:19]
	v_cvt_f32_u32_e32 v4, v2
	s_waitcnt vmcnt(0)
	v_readfirstlane_b32 s12, v3
	v_sub_u32_e32 v3, 0, v2
	v_rcp_iflag_f32_e32 v4, v4
	v_add_u32_e32 v5, s12, v1
	v_mul_f32_e32 v4, 0x4f7ffffe, v4
	v_cvt_u32_f32_e32 v4, v4
	v_mul_lo_u32 v1, v3, v4
	v_mul_hi_u32 v1, v4, v1
	v_add_u32_e32 v1, v4, v1
	v_mul_hi_u32 v1, v5, v1
	v_mul_lo_u32 v3, v1, v2
	v_sub_u32_e32 v3, v5, v3
	v_add_u32_e32 v4, 1, v1
	v_cmp_ge_u32_e32 vcc, v3, v2
	s_nop 1
	v_cndmask_b32_e32 v1, v1, v4, vcc
	v_sub_u32_e32 v4, v3, v2
	v_cndmask_b32_e32 v3, v3, v4, vcc
	v_add_u32_e32 v4, 1, v1
	v_cmp_ge_u32_e32 vcc, v3, v2
	v_add_u32_e32 v3, 1, v5
	s_nop 0
	v_cndmask_b32_e32 v1, v1, v4, vcc
	v_mul_lo_u32 v4, v2, v1
	v_add_u32_e32 v2, v4, v2
	v_cmp_ne_u32_e32 vcc, v3, v2
	s_and_saveexec_b64 s[12:13], vcc
	s_xor_b64 s[12:13], exec, s[12:13]
	s_cbranch_execz .LBB0_76
	s_waitcnt lgkmcnt(0)
	buffer_inv sc1
	v_cmp_eq_u32_e32 vcc, v5, v4
	s_cbranch_vccz .Lfwb_0
	buffer_wbl2 sc1
.Lfwb_0:
	v_mov_b32_e32 v0, 0x2000
	global_load_dword v0, v0, s[4:5] offset:1024 sc1
	s_add_u32 s34, s4, 0x2400
	s_addc_u32 s35, s5, 0
	s_waitcnt vmcnt(0)
	v_cmp_eq_u32_e32 vcc, v0, v1
	s_and_saveexec_b64 s[18:19], vcc
	s_cbranch_execz .LBB0_75
	s_add_u32 s30, s24, 0x22204300
	s_addc_u32 s31, s25, 0
	s_mov_b32 s56, 1
	s_mov_b64 s[36:37], 0
	v_mov_b32_e32 v0, 0
	s_branch .LBB0_66

.LBB0_160:
	s_or_b64 exec, exec, s[30:31]
	v_cvt_f32_u32_e32 v4, v2
	s_waitcnt vmcnt(0)
	v_readfirstlane_b32 s8, v3
	v_sub_u32_e32 v3, 0, v2
	v_rcp_iflag_f32_e32 v4, v4
	v_add_u32_e32 v5, s8, v1
	v_mul_f32_e32 v4, 0x4f7ffffe, v4
	v_cvt_u32_f32_e32 v4, v4
	v_mul_lo_u32 v1, v3, v4
	v_mul_hi_u32 v1, v4, v1
	v_add_u32_e32 v1, v4, v1
	v_mul_hi_u32 v1, v5, v1
	v_mul_lo_u32 v3, v1, v2
	v_sub_u32_e32 v3, v5, v3
	v_add_u32_e32 v4, 1, v1
	v_cmp_ge_u32_e32 vcc, v3, v2
	s_nop 1
	v_cndmask_b32_e32 v1, v1, v4, vcc
	v_sub_u32_e32 v4, v3, v2
	v_cndmask_b32_e32 v3, v3, v4, vcc
	v_add_u32_e32 v4, 1, v1
	v_cmp_ge_u32_e32 vcc, v3, v2
	v_add_u32_e32 v3, 1, v5
	s_nop 0
	v_cndmask_b32_e32 v1, v1, v4, vcc
	v_mul_lo_u32 v4, v2, v1
	v_add_u32_e32 v2, v4, v2
	v_cmp_ne_u32_e32 vcc, v3, v2
	s_and_saveexec_b64 s[8:9], vcc
	s_xor_b64 s[8:9], exec, s[8:9]
	s_cbranch_execz .LBB0_174
	s_waitcnt lgkmcnt(0)
	buffer_inv sc1
	v_cmp_eq_u32_e32 vcc, v5, v4
	s_cbranch_vccz .Lfwb_1
	buffer_wbl2 sc1
.Lfwb_1:
	v_mov_b32_e32 v0, 0x2000
	global_load_dword v0, v0, s[4:5] offset:1024 sc1
	s_add_u32 s36, s4, 0x2400
	s_addc_u32 s37, s5, 0
	s_waitcnt vmcnt(0)
	v_cmp_eq_u32_e32 vcc, v0, v1
	s_and_saveexec_b64 s[30:31], vcc
	s_cbranch_execz .LBB0_173
	s_add_u32 s34, s24, 0x22204300
	s_addc_u32 s35, s25, 0
	s_mov_b32 s54, 1
	s_mov_b64 s[40:41], 0
	v_mov_b32_e32 v0, 0
	s_branch .LBB0_164

.LBB0_592:
	s_or_b64 exec, exec, s[10:11]
	v_cvt_f32_u32_e32 v4, v2
	s_waitcnt vmcnt(0)
	v_readfirstlane_b32 s8, v3
	v_sub_u32_e32 v3, 0, v2
	v_rcp_iflag_f32_e32 v4, v4
	v_add_u32_e32 v5, s8, v1
	v_mul_f32_e32 v4, 0x4f7ffffe, v4
	v_cvt_u32_f32_e32 v4, v4
	v_mul_lo_u32 v1, v3, v4
	v_mul_hi_u32 v1, v4, v1
	v_add_u32_e32 v1, v4, v1
	v_mul_hi_u32 v1, v5, v1
	v_mul_lo_u32 v3, v1, v2
	v_sub_u32_e32 v3, v5, v3
	v_add_u32_e32 v4, 1, v1
	v_cmp_ge_u32_e32 vcc, v3, v2
	s_nop 1
	v_cndmask_b32_e32 v1, v1, v4, vcc
	v_sub_u32_e32 v4, v3, v2
	v_cndmask_b32_e32 v3, v3, v4, vcc
	v_add_u32_e32 v4, 1, v1
	v_cmp_ge_u32_e32 vcc, v3, v2
	v_add_u32_e32 v3, 1, v5
	s_nop 0
	v_cndmask_b32_e32 v1, v1, v4, vcc
	v_mul_lo_u32 v4, v2, v1
	v_add_u32_e32 v2, v4, v2
	v_cmp_ne_u32_e32 vcc, v3, v2
	s_and_saveexec_b64 s[8:9], vcc
	s_xor_b64 s[8:9], exec, s[8:9]
	s_cbranch_execz .LBB0_606
	s_waitcnt lgkmcnt(0)
	buffer_inv sc1
	v_cmp_eq_u32_e32 vcc, v5, v4
	s_cbranch_vccz .Lfwb_5
	buffer_wbl2 sc1
.Lfwb_5:
	v_mov_b32_e32 v0, 0x2000
	global_load_dword v0, v0, s[4:5] offset:1024 sc1
	s_add_u32 s34, s4, 0x2400
	s_addc_u32 s35, s5, 0
	s_waitcnt vmcnt(0)
	v_cmp_eq_u32_e32 vcc, v0, v1
	s_and_saveexec_b64 s[10:11], vcc
	s_cbranch_execz .LBB0_605
	s_add_u32 s30, s24, 0x22204300
	s_addc_u32 s31, s25, 0
	s_mov_b32 s50, 1
	s_mov_b64 s[36:37], 0
	v_mov_b32_e32 v0, 0
	s_branch .LBB0_596

.LBB0_863:
	s_or_b64 exec, exec, s[10:11]
	v_cvt_f32_u32_e32 v4, v2
	s_waitcnt vmcnt(0)
	v_readfirstlane_b32 s7, v3
	v_sub_u32_e32 v3, 0, v2
	v_rcp_iflag_f32_e32 v4, v4
	v_add_u32_e32 v5, s7, v1
	v_mul_f32_e32 v4, 0x4f7ffffe, v4
	v_cvt_u32_f32_e32 v4, v4
	v_mul_lo_u32 v1, v3, v4
	v_mul_hi_u32 v1, v4, v1
	v_add_u32_e32 v1, v4, v1
	v_mul_hi_u32 v1, v5, v1
	v_mul_lo_u32 v3, v1, v2
	v_sub_u32_e32 v3, v5, v3
	v_add_u32_e32 v4, 1, v1
	v_cmp_ge_u32_e32 vcc, v3, v2
	s_nop 1
	v_cndmask_b32_e32 v1, v1, v4, vcc
	v_sub_u32_e32 v4, v3, v2
	v_cndmask_b32_e32 v3, v3, v4, vcc
	v_add_u32_e32 v4, 1, v1
	v_cmp_ge_u32_e32 vcc, v3, v2
	v_add_u32_e32 v3, 1, v5
	s_nop 0
	v_cndmask_b32_e32 v1, v1, v4, vcc
	v_mul_lo_u32 v4, v2, v1
	v_add_u32_e32 v2, v4, v2
	v_cmp_ne_u32_e32 vcc, v3, v2
	s_and_saveexec_b64 s[8:9], vcc
	s_xor_b64 s[8:9], exec, s[8:9]
	s_cbranch_execz .LBB0_877
	s_waitcnt lgkmcnt(0)
	buffer_inv sc1
	v_cmp_eq_u32_e32 vcc, v5, v4
	s_cbranch_vccz .Lfwb_7
	buffer_wbl2 sc1
.Lfwb_7:
	v_mov_b32_e32 v0, 0x2000
	global_load_dword v0, v0, s[4:5] offset:1024 sc1
	s_add_u32 s16, s4, 0x2400
	s_addc_u32 s17, s5, 0
	s_waitcnt vmcnt(0)
	v_cmp_eq_u32_e32 vcc, v0, v1
	s_and_saveexec_b64 s[10:11], vcc
	s_cbranch_execz .LBB0_876
	s_add_u32 s14, s24, 0x22204300
	s_addc_u32 s15, s25, 0
	s_mov_b32 s46, 1
	s_mov_b64 s[30:31], 0
	v_mov_b32_e32 v0, 0
	s_branch .LBB0_867

.Lfwb_10:
	v_mov_b32_e32 v0, 0x2000
	global_load_dword v0, v0, s[4:5] offset:1024 sc1
	s_add_u32 s16, s4, 0x2400
	s_addc_u32 s17, s5, 0
	s_waitcnt vmcnt(0)
	v_cmp_eq_u32_e32 vcc, v0, v1
	s_and_saveexec_b64 s[10:11], vcc
	s_cbranch_execz .LBB0_1172
	s_add_u32 s14, s24, 0x22204300
	s_addc_u32 s15, s25, 0
	s_mov_b32 s42, 1
	s_mov_b64 s[20:21], 0
	v_mov_b32_e32 v0, 0
	s_branch .LBB0_1163

.Lfwb_12:
	v_mov_b32_e32 v0, 0x2000
	global_load_dword v0, v0, s[4:5] offset:1024 sc1
	s_add_u32 s16, s4, 0x2400
	s_addc_u32 s17, s5, 0
	s_waitcnt vmcnt(0)
	v_cmp_eq_u32_e32 vcc, v0, v1
	s_and_saveexec_b64 s[10:11], vcc
	s_cbranch_execz .LBB0_1381
	s_add_u32 s14, s24, 0x22204300
	s_addc_u32 s15, s25, 0
	s_mov_b32 s7, 1
	s_mov_b64 s[20:21], 0
	v_mov_b32_e32 v0, 0
	s_branch .LBB0_1372

.LBB0_1483:
	s_or_b64 exec, exec, s[6:7]
	v_cvt_f32_u32_e32 v4, v2
	s_waitcnt vmcnt(0)
	v_readfirstlane_b32 s4, v3
	v_sub_u32_e32 v3, 0, v2
	v_rcp_iflag_f32_e32 v4, v4
	v_add_u32_e32 v5, s4, v1
	v_mul_f32_e32 v4, 0x4f7ffffe, v4
	v_cvt_u32_f32_e32 v4, v4
	v_mul_lo_u32 v1, v3, v4
	v_mul_hi_u32 v1, v4, v1
	v_add_u32_e32 v1, v4, v1
	v_mul_hi_u32 v1, v5, v1
	v_mul_lo_u32 v3, v1, v2
	v_sub_u32_e32 v3, v5, v3
	v_add_u32_e32 v4, 1, v1
	v_cmp_ge_u32_e32 vcc, v3, v2
	s_nop 1
	v_cndmask_b32_e32 v1, v1, v4, vcc
	v_sub_u32_e32 v4, v3, v2
	v_cndmask_b32_e32 v3, v3, v4, vcc
	v_add_u32_e32 v4, 1, v1
	v_cmp_ge_u32_e32 vcc, v3, v2
	v_add_u32_e32 v3, 1, v5
	s_nop 0
	v_cndmask_b32_e32 v1, v1, v4, vcc
	v_mul_lo_u32 v4, v2, v1
	v_add_u32_e32 v2, v4, v2
	v_cmp_ne_u32_e32 vcc, v3, v2
	s_and_saveexec_b64 s[4:5], vcc
	s_xor_b64 s[4:5], exec, s[4:5]
	s_cbranch_execz .LBB0_1497
	s_waitcnt lgkmcnt(0)
	buffer_inv sc1
	v_cmp_eq_u32_e32 vcc, v5, v4
	s_cbranch_vccz .Lfwb_13
	buffer_wbl2 sc1
.Lfwb_13:
	v_mov_b32_e32 v0, 0x2000
	global_load_dword v0, v0, s[2:3] offset:1024 sc1
	s_add_u32 s10, s2, 0x2400
	s_addc_u32 s11, s3, 0
	s_waitcnt vmcnt(0)
	v_cmp_eq_u32_e32 vcc, v0, v1
	s_and_saveexec_b64 s[6:7], vcc
	s_cbranch_execz .LBB0_1496
	s_add_u32 s8, s24, 0x22204300
	s_addc_u32 s9, s25, 0
	s_mov_b32 s22, 1
	s_mov_b64 s[12:13], 0
	v_mov_b32_e32 v0, 0
	s_branch .LBB0_1487
